# down/out/o epilogues: the waiting wave half issues its residual-tile loads before the epilogue-alignment barrier so their latency overlaps the wait
# speedup vs baseline: 1.0133x; 1.0018x over previous
.Lpeelx_434:
.LBB7_435:
.LBB7_437:
	s_waitcnt lgkmcnt(0)
	v_lshl_or_b32 v2, s10, 8, v206
	v_lshl_add_u32 v184, s89, 8, v204
	v_ashrrev_i32_e32 v3, 31, v2
	v_lshlrev_b64 v[132:133], 1, v[2:3]
	v_ashrrev_i32_e32 v185, 31, v184
	v_lshl_add_u64 v[190:191], s[68:69], 0, v[132:133]
	v_lshlrev_b64 v[134:135], 11, v[184:185]
	v_lshl_add_u64 v[136:137], v[190:191], 0, v[134:135]
	global_load_dwordx4 v[196:199], v[136:137], off
	global_load_dwordx4 v[208:211], v[136:137], off offset:256
	v_or_b32_e32 v192, 16, v184
	v_or_b32_e32 v186, 32, v184
	v_or_b32_e32 v156, 48, v184
	v_ashrrev_i32_e32 v193, 31, v192
	v_ashrrev_i32_e32 v187, 31, v186
	v_ashrrev_i32_e32 v157, 31, v156
	v_lshlrev_b64 v[194:195], 11, v[192:193]
	v_lshlrev_b64 v[188:189], 11, v[186:187]
	v_lshlrev_b64 v[158:159], 11, v[156:157]
	v_lshl_add_u64 v[134:135], s[68:69], 0, v[134:135]
	v_lshl_add_u64 v[136:137], v[190:191], 0, v[194:195]
	v_lshl_add_u64 v[138:139], v[190:191], 0, v[188:189]
	v_lshl_add_u64 v[170:171], v[190:191], 0, v[158:159]
	v_lshl_add_u64 v[172:173], v[134:135], 0, v[132:133]
	global_load_dwordx4 v[152:155], v[136:137], off
	global_load_dwordx4 v[148:151], v[136:137], off offset:256
	global_load_dwordx4 v[144:147], v[138:139], off
	global_load_dwordx4 v[140:143], v[138:139], off offset:256
	s_nop 0
	global_load_dwordx4 v[136:139], v[170:171], off
	global_load_dwordx4 v[132:135], v[170:171], off offset:256
	v_add_u32_e32 v248, 0x80, v184
	v_ashrrev_i32_e32 v249, 31, v248
	v_lshlrev_b64 v[248:249], 11, v[248:249]
	v_lshl_add_u64 v[248:249], v[190:191], 0, v[248:249]
	global_load_dwordx4 v[232:235], v[248:249], off
	global_load_dwordx4 v[236:239], v[248:249], off offset:256
	s_mov_b64 s[72:73], 0x8000
	v_lshl_add_u64 v[248:249], v[248:249], 0, s[72:73]
	global_load_dwordx4 v[240:243], v[248:249], off
	global_load_dwordx4 v[244:247], v[248:249], off offset:256
	s_lshl_b32 s16, s10, 2
	s_ashr_i32 s17, s16, 31
	s_and_b64 vcc, exec, s[12:13]
	s_cbranch_vccz .Lresid_nb_435
	s_barrier
.Lresid_nb_435:
	s_waitcnt vmcnt(0)
	v_lshlrev_b32_e32 v212, 16, v198
	v_and_b32_e32 v213, 0xffff0000, v198
	v_lshlrev_b32_e32 v198, 16, v199
	v_and_b32_e32 v199, 0xffff0000, v199
	v_lshlrev_b32_e32 v170, 16, v196
	v_and_b32_e32 v171, 0xffff0000, v196
	v_lshlrev_b32_e32 v196, 16, v197
	v_and_b32_e32 v197, 0xffff0000, v197
	v_pk_fma_f32 v[220:221], v[126:127], 0.5, v[198:199] op_sel_hi:[1,0,1]
	v_pk_fma_f32 v[198:199], v[124:125], 0.5, v[212:213] op_sel_hi:[1,0,1]
	v_lshlrev_b32_e32 v214, 16, v208
	v_and_b32_e32 v215, 0xffff0000, v208
	v_lshlrev_b32_e32 v208, 16, v209
	v_and_b32_e32 v209, 0xffff0000, v209
	v_lshlrev_b32_e32 v216, 16, v210
	v_and_b32_e32 v217, 0xffff0000, v210
	v_lshlrev_b32_e32 v210, 16, v211
	v_and_b32_e32 v211, 0xffff0000, v211
	v_pk_fma_f32 v[218:219], v[130:131], 0.5, v[196:197] op_sel_hi:[1,0,1]
	v_pk_fma_f32 v[170:171], v[128:129], 0.5, v[170:171] op_sel_hi:[1,0,1]
	v_pk_fma_f32 v[208:209], v[98:99], 0.5, v[208:209] op_sel_hi:[1,0,1]
	v_cvt_pk_bf16_f32 v196, v170, v171
	v_cvt_pk_bf16_f32 v197, v218, v219
	v_cvt_pk_bf16_f32 v198, v198, v199
	v_cvt_pk_bf16_f32 v199, v220, v221
	v_pk_fma_f32 v[212:213], v[96:97], 0.5, v[214:215] op_sel_hi:[1,0,1]
	v_pk_fma_f32 v[214:215], v[94:95], 0.5, v[210:211] op_sel_hi:[1,0,1]
	global_store_dwordx4 v[172:173], v[196:199], off
	v_lshlrev_b32_e32 v0, 16, v196
	v_and_b32_e32 v170, 0xffff0000, v196
	v_lshlrev_b32_e32 v171, 16, v197
	v_and_b32_e32 v196, 0xffff0000, v197
	v_lshlrev_b32_e32 v197, 16, v198
	v_and_b32_e32 v198, 0xffff0000, v198
	v_lshlrev_b32_e32 v218, 16, v199
	v_and_b32_e32 v199, 0xffff0000, v199
	v_pk_fma_f32 v[216:217], v[92:93], 0.5, v[216:217] op_sel_hi:[1,0,1]
	v_cvt_pk_bf16_f32 v210, v212, v213
	v_cvt_pk_bf16_f32 v211, v208, v209
	v_mul_f32_e32 v170, v170, v170
	v_cvt_pk_bf16_f32 v212, v216, v217
	v_cvt_pk_bf16_f32 v213, v214, v215
	v_mul_f32_e32 v196, v196, v196
	v_mul_f32_e32 v198, v198, v198
	v_mul_f32_e32 v199, v199, v199
	v_and_b32_e32 v209, 0xffff0000, v210
	v_and_b32_e32 v215, 0xffff0000, v211
	v_lshlrev_b32_e32 v208, 16, v210
	v_lshlrev_b32_e32 v214, 16, v211
	v_fmac_f32_e32 v170, v0, v0
	v_fmac_f32_e32 v196, v171, v171
	v_fmac_f32_e32 v198, v197, v197
	v_fmac_f32_e32 v199, v218, v218
	v_mul_f32_e32 v0, v209, v209
	v_mul_f32_e32 v171, v215, v215
	v_and_b32_e32 v217, 0xffff0000, v212
	v_and_b32_e32 v220, 0xffff0000, v213
	v_add_f32_e32 v170, v170, v196
	v_add_f32_e32 v196, v198, v199
	v_fmac_f32_e32 v0, v208, v208
	v_fmac_f32_e32 v171, v214, v214
	v_lshlrev_b32_e32 v216, 16, v212
	v_lshlrev_b32_e32 v219, 16, v213
	v_add_f32_e32 v170, v170, v196
	v_add_f32_e32 v0, v0, v171
	v_mul_f32_e32 v171, v217, v217
	v_mul_f32_e32 v196, v220, v220
	v_fmac_f32_e32 v171, v216, v216
	v_fmac_f32_e32 v196, v219, v219
	v_add_f32_e32 v171, v171, v196
	v_add_f32_e32 v0, v0, v171
	v_and_b32_e32 v171, 64, v163
	v_add_f32_e32 v170, v170, v0
	v_xor_b32_e32 v0, 16, v163
	v_add_u32_e32 v171, 64, v171
	v_cmp_lt_i32_e32 vcc, v0, v171
	global_store_dwordx4 v[172:173], v[210:213], off offset:256
	s_nop 0
	v_cndmask_b32_e32 v0, v163, v0, vcc
	v_lshlrev_b32_e32 v0, 2, v0
	v_mov_b32_e32 v196, v170
	s_nop 1
	v_permlane16_swap_b32_e32 v170, v196
	s_waitcnt lgkmcnt(0)
	v_add_f32_e32 v196, v170, v196
	v_xor_b32_e32 v170, 32, v163
	v_cmp_lt_i32_e32 vcc, v170, v171
	s_nop 1
	v_cndmask_b32_e32 v170, v163, v170, vcc
	v_lshlrev_b32_e32 v208, 2, v170
	v_mov_b32_e32 v197, v196
	s_nop 1
	v_permlane32_swap_b32_e32 v196, v197
	s_and_saveexec_b64 s[72:73], s[40:41]
	s_cbranch_execz .LBB7_439
	v_lshlrev_b64 v[170:171], 6, v[184:185]
	v_lshl_add_u64 v[170:171], s[66:67], 0, v[170:171]
	v_lshl_add_u64 v[170:171], s[16:17], 2, v[170:171]
	s_lshl_b32 s20, s96, 2
	v_lshl_add_u64 v[170:171], v[170:171], 0, s[20:21]
	s_waitcnt lgkmcnt(0)
	v_add_f32_e32 v172, v196, v197
	global_store_dword v[170:171], v172, off

.Lpeelx_1104:
.LBB7_1105:
.LBB7_1107:
	s_waitcnt lgkmcnt(0)
	v_lshl_or_b32 v2, s57, 8, v206
	v_lshl_add_u32 v184, s88, 8, v204
	v_ashrrev_i32_e32 v3, 31, v2
	v_lshlrev_b64 v[132:133], 1, v[2:3]
	v_ashrrev_i32_e32 v185, 31, v184
	v_lshl_add_u64 v[190:191], s[68:69], 0, v[132:133]
	v_lshlrev_b64 v[134:135], 11, v[184:185]
	v_lshl_add_u64 v[136:137], v[190:191], 0, v[134:135]
	global_load_dwordx4 v[196:199], v[136:137], off
	global_load_dwordx4 v[208:211], v[136:137], off offset:256
	v_or_b32_e32 v192, 16, v184
	v_or_b32_e32 v186, 32, v184
	v_or_b32_e32 v156, 48, v184
	v_ashrrev_i32_e32 v193, 31, v192
	v_ashrrev_i32_e32 v187, 31, v186
	v_ashrrev_i32_e32 v157, 31, v156
	v_lshlrev_b64 v[194:195], 11, v[192:193]
	v_lshlrev_b64 v[188:189], 11, v[186:187]
	v_lshlrev_b64 v[158:159], 11, v[156:157]
	v_lshl_add_u64 v[134:135], s[68:69], 0, v[134:135]
	v_lshl_add_u64 v[136:137], v[190:191], 0, v[194:195]
	v_lshl_add_u64 v[138:139], v[190:191], 0, v[188:189]
	v_lshl_add_u64 v[170:171], v[190:191], 0, v[158:159]
	v_lshl_add_u64 v[172:173], v[134:135], 0, v[132:133]
	global_load_dwordx4 v[152:155], v[136:137], off
	global_load_dwordx4 v[148:151], v[136:137], off offset:256
	global_load_dwordx4 v[144:147], v[138:139], off
	global_load_dwordx4 v[140:143], v[138:139], off offset:256
	s_nop 0
	global_load_dwordx4 v[136:139], v[170:171], off
	global_load_dwordx4 v[132:135], v[170:171], off offset:256
	v_add_u32_e32 v248, 0x80, v184
	v_ashrrev_i32_e32 v249, 31, v248
	v_lshlrev_b64 v[248:249], 11, v[248:249]
	v_lshl_add_u64 v[248:249], v[190:191], 0, v[248:249]
	global_load_dwordx4 v[232:235], v[248:249], off
	global_load_dwordx4 v[236:239], v[248:249], off offset:256
	s_mov_b64 s[72:73], 0x8000
	v_lshl_add_u64 v[248:249], v[248:249], 0, s[72:73]
	global_load_dwordx4 v[240:243], v[248:249], off
	global_load_dwordx4 v[244:247], v[248:249], off offset:256
	s_and_b64 vcc, exec, s[6:7]
	s_cbranch_vccz .Lresid_nb_1105
	s_barrier
.Lresid_nb_1105:
	s_waitcnt vmcnt(0)
	v_lshlrev_b32_e32 v212, 16, v198
	v_and_b32_e32 v213, 0xffff0000, v198
	v_lshlrev_b32_e32 v198, 16, v199
	v_and_b32_e32 v199, 0xffff0000, v199
	v_lshlrev_b32_e32 v170, 16, v196
	v_and_b32_e32 v171, 0xffff0000, v196
	v_lshlrev_b32_e32 v196, 16, v197
	v_and_b32_e32 v197, 0xffff0000, v197
	v_pk_add_f32 v[220:221], v[126:127], v[198:199]
	v_pk_add_f32 v[198:199], v[124:125], v[212:213]
	v_lshlrev_b32_e32 v214, 16, v208
	v_and_b32_e32 v215, 0xffff0000, v208
	v_lshlrev_b32_e32 v208, 16, v209
	v_and_b32_e32 v209, 0xffff0000, v209
	v_lshlrev_b32_e32 v216, 16, v210
	v_and_b32_e32 v217, 0xffff0000, v210
	v_lshlrev_b32_e32 v210, 16, v211
	v_and_b32_e32 v211, 0xffff0000, v211
	v_pk_add_f32 v[218:219], v[130:131], v[196:197]
	v_pk_add_f32 v[170:171], v[128:129], v[170:171]
	v_pk_add_f32 v[208:209], v[98:99], v[208:209]
	v_cvt_pk_bf16_f32 v196, v170, v171
	v_cvt_pk_bf16_f32 v197, v218, v219
	v_cvt_pk_bf16_f32 v198, v198, v199
	v_cvt_pk_bf16_f32 v199, v220, v221
	v_pk_add_f32 v[212:213], v[96:97], v[214:215]
	v_pk_add_f32 v[214:215], v[94:95], v[210:211]
	global_store_dwordx4 v[172:173], v[196:199], off
	v_lshlrev_b32_e32 v0, 16, v196
	v_and_b32_e32 v170, 0xffff0000, v196
	v_lshlrev_b32_e32 v171, 16, v197
	v_and_b32_e32 v196, 0xffff0000, v197
	v_lshlrev_b32_e32 v197, 16, v198
	v_and_b32_e32 v198, 0xffff0000, v198
	v_lshlrev_b32_e32 v218, 16, v199
	v_and_b32_e32 v199, 0xffff0000, v199
	v_pk_add_f32 v[216:217], v[92:93], v[216:217]
	v_cvt_pk_bf16_f32 v210, v212, v213
	v_cvt_pk_bf16_f32 v211, v208, v209
	v_mul_f32_e32 v170, v170, v170
	v_cvt_pk_bf16_f32 v212, v216, v217
	v_cvt_pk_bf16_f32 v213, v214, v215
	v_mul_f32_e32 v196, v196, v196
	v_mul_f32_e32 v198, v198, v198
	v_mul_f32_e32 v199, v199, v199
	v_and_b32_e32 v209, 0xffff0000, v210
	v_and_b32_e32 v215, 0xffff0000, v211
	v_lshlrev_b32_e32 v208, 16, v210
	v_lshlrev_b32_e32 v214, 16, v211
	v_fmac_f32_e32 v170, v0, v0
	v_fmac_f32_e32 v196, v171, v171
	v_fmac_f32_e32 v198, v197, v197
	v_fmac_f32_e32 v199, v218, v218
	v_mul_f32_e32 v0, v209, v209
	v_mul_f32_e32 v171, v215, v215
	v_and_b32_e32 v217, 0xffff0000, v212
	v_and_b32_e32 v220, 0xffff0000, v213
	v_add_f32_e32 v170, v170, v196
	v_add_f32_e32 v196, v198, v199
	v_fmac_f32_e32 v0, v208, v208
	v_fmac_f32_e32 v171, v214, v214
	v_lshlrev_b32_e32 v216, 16, v212
	v_lshlrev_b32_e32 v219, 16, v213
	v_add_f32_e32 v170, v170, v196
	v_add_f32_e32 v0, v0, v171
	v_mul_f32_e32 v171, v217, v217
	v_mul_f32_e32 v196, v220, v220
	v_fmac_f32_e32 v171, v216, v216
	v_fmac_f32_e32 v196, v219, v219
	v_add_f32_e32 v171, v171, v196
	v_add_f32_e32 v0, v0, v171
	v_and_b32_e32 v171, 64, v163
	v_add_f32_e32 v170, v170, v0
	v_xor_b32_e32 v0, 16, v163
	v_add_u32_e32 v171, 64, v171
	v_cmp_lt_i32_e32 vcc, v0, v171
	global_store_dwordx4 v[172:173], v[210:213], off offset:256
	s_nop 0
	v_cndmask_b32_e32 v0, v163, v0, vcc
	v_lshlrev_b32_e32 v0, 2, v0
	v_mov_b32_e32 v196, v170
	s_nop 1
	v_permlane16_swap_b32_e32 v170, v196
	s_waitcnt lgkmcnt(0)
	v_add_f32_e32 v196, v170, v196
	v_xor_b32_e32 v170, 32, v163
	v_cmp_lt_i32_e32 vcc, v170, v171
	s_nop 1
	v_cndmask_b32_e32 v170, v163, v170, vcc
	v_lshlrev_b32_e32 v208, 2, v170
	v_mov_b32_e32 v197, v196
	s_nop 1
	v_permlane32_swap_b32_e32 v196, v197
	s_lshl_b32 vcc_lo, s57, 2
	s_ashr_i32 vcc_hi, vcc_lo, 31
	s_and_saveexec_b64 s[72:73], s[40:41]
	s_cbranch_execz .LBB7_1109
	v_lshlrev_b64 v[170:171], 6, v[184:185]
	v_lshl_add_u64 v[170:171], s[66:67], 0, v[170:171]
	v_lshl_add_u64 v[170:171], vcc, 2, v[170:171]
	s_lshl_b32 s20, s92, 2
	v_lshl_add_u64 v[170:171], v[170:171], 0, s[20:21]
	s_waitcnt lgkmcnt(0)
	v_add_f32_e32 v172, v196, v197
	global_store_dword v[170:171], v172, off
